# NA band step: 16 serialized exec-masked ds_read_b32 bias fetches replaced by 8 ds_read2_b32 issued behind the K reads, bias masked to -inf beside the QK MFMAs, 16 plain adds
# speedup vs baseline: 1.0216x; 1.0216x over previous
.LBB0_1086:
	s_cmp_gt_u32 s41, 3
	s_mov_b64 s[12:13], -1
	s_cbranch_scc0 .LBB0_1125
	s_add_i32 s41, s22, s41
	s_add_i32 s42, s41, -4
	v_cmp_ge_i32_e32 vcc, s41, v135
	v_cmp_lt_i32_e64 s[12:13], s42, v136
	s_and_b64 s[12:13], vcc, s[12:13]
	v_mov_b64_e32 v[62:63], v[30:31]
	s_andn2_b64 vcc, exec, s[12:13]
	v_mov_b32_e32 v144, v139
	v_mov_b32_e32 v141, v140
	v_mov_b64_e32 v[60:61], v[28:29]
	v_mov_b64_e32 v[58:59], v[26:27]
	v_mov_b64_e32 v[56:57], v[24:25]
	v_mov_b64_e32 v[54:55], v[22:23]
	v_mov_b64_e32 v[52:53], v[20:21]
	v_mov_b64_e32 v[50:51], v[18:19]
	v_mov_b64_e32 v[48:49], v[16:17]
	v_mov_b64_e32 v[46:47], v[14:15]
	v_mov_b64_e32 v[44:45], v[12:13]
	v_mov_b64_e32 v[42:43], v[10:11]
	v_mov_b64_e32 v[40:41], v[8:9]
	v_mov_b64_e32 v[38:39], v[6:7]
	v_mov_b64_e32 v[36:37], v[4:5]
	v_mov_b64_e32 v[34:35], v[2:3]
	v_mov_b64_e32 v[32:33], v[0:1]
	s_cbranch_vccnz .LBB0_1123
	v_add_u32_e32 v36, s40, v114
	v_add_u32_e32 v32, v36, v117
	v_add_u32_e32 v37, v36, v118
	ds_read_b128 v[32:35], v32
	ds_read_b128 v[48:51], v37
	v_add_u32_e32 v37, v36, v119
	v_add_u32_e32 v36, v36, v120
	ds_read_b128 v[52:55], v37
	ds_read_b128 v[56:59], v36
	ds_read2_b32 v[240:241], v138 offset1:1
	ds_read2_b32 v[242:243], v138 offset0:2 offset1:3
	ds_read2_b32 v[244:245], v138 offset0:8 offset1:9
	ds_read2_b32 v[246:247], v138 offset0:10 offset1:11
	ds_read2_b32 v[248:249], v138 offset0:16 offset1:17
	ds_read2_b32 v[250:251], v138 offset0:18 offset1:19
	ds_read2_b32 v[252:253], v138 offset0:24 offset1:25
	ds_read2_b32 v[254:255], v138 offset0:26 offset1:27
	v_cmp_ge_i32_e32 vcc, s41, v134
	v_cmp_lt_i32_e64 s[12:13], s42, v137
	s_and_b64 vcc, vcc, s[12:13]
	v_cndmask_b32_e32 v159, v133, v115, vcc
	v_mov_b32_e32 v157, 0xff800000
	s_waitcnt lgkmcnt(11)
	v_mfma_f32_32x32x16_bf16 v[32:47], v[32:35], v[64:67], 0
	s_waitcnt lgkmcnt(10)
	v_mfma_f32_32x32x16_bf16 v[32:47], v[48:51], v[68:71], v[32:47]
	s_waitcnt lgkmcnt(9)
	v_mfma_f32_32x32x16_bf16 v[32:47], v[52:55], v[72:75], v[32:47]
	s_waitcnt lgkmcnt(0)
	v_cmp_gt_u32_e32 vcc, 16, v159
	v_cndmask_b32_e32 v240, v157, v240, vcc
	v_add_u32_e32 v158, 1, v159
	v_cmp_gt_u32_e32 vcc, 16, v158
	v_cndmask_b32_e32 v241, v157, v241, vcc
	v_add_u32_e32 v158, 2, v159
	v_cmp_gt_u32_e32 vcc, 16, v158
	v_cndmask_b32_e32 v242, v157, v242, vcc
	v_add_u32_e32 v158, 3, v159
	v_cmp_gt_u32_e32 vcc, 16, v158
	v_cndmask_b32_e32 v243, v157, v243, vcc
	v_add_u32_e32 v158, 8, v159
	v_cmp_gt_u32_e32 vcc, 16, v158
	v_cndmask_b32_e32 v244, v157, v244, vcc
	v_add_u32_e32 v158, 9, v159
	v_cmp_gt_u32_e32 vcc, 16, v158
	v_cndmask_b32_e32 v245, v157, v245, vcc
	v_add_u32_e32 v158, 10, v159
	v_cmp_gt_u32_e32 vcc, 16, v158
	v_cndmask_b32_e32 v246, v157, v246, vcc
	v_add_u32_e32 v158, 11, v159
	v_cmp_gt_u32_e32 vcc, 16, v158
	v_cndmask_b32_e32 v247, v157, v247, vcc
	v_mfma_f32_32x32x16_bf16 v[32:47], v[56:59], v[76:79], v[32:47]
	v_cmp_lt_u32_e32 vcc, s36, v159
	v_cndmask_b32_e32 v248, v157, v248, vcc
	v_add_u32_e32 v158, 17, v159
	v_cmp_gt_u32_e32 vcc, 16, v158
	v_cndmask_b32_e32 v249, v157, v249, vcc
	v_add_u32_e32 v158, 18, v159
	v_cmp_gt_u32_e32 vcc, 16, v158
	v_cndmask_b32_e32 v250, v157, v250, vcc
	v_add_u32_e32 v158, 19, v159
	v_cmp_gt_u32_e32 vcc, 16, v158
	v_cndmask_b32_e32 v251, v157, v251, vcc
	v_add_u32_e32 v158, 24, v159
	v_cmp_gt_u32_e32 vcc, 16, v158
	v_cndmask_b32_e32 v252, v157, v252, vcc
	v_add_u32_e32 v158, 25, v159
	v_cmp_gt_u32_e32 vcc, 16, v158
	v_cndmask_b32_e32 v253, v157, v253, vcc
	v_add_u32_e32 v158, 26, v159
	v_cmp_gt_u32_e32 vcc, 16, v158
	v_cndmask_b32_e32 v254, v157, v254, vcc
	v_add_u32_e32 v158, 27, v159
	v_cmp_gt_u32_e32 vcc, 16, v158
	v_cndmask_b32_e32 v255, v157, v255, vcc
	v_add_f32_e32 v142, v32, v240
	v_add_f32_e32 v141, v33, v241
	v_add_f32_e32 v145, v34, v242
	v_add_f32_e32 v143, v35, v243
	v_add_f32_e32 v147, v36, v244
	v_add_f32_e32 v146, v37, v245
	v_add_f32_e32 v149, v38, v246
	v_add_f32_e32 v148, v39, v247
	v_add_f32_e32 v151, v40, v248
	v_add_f32_e32 v150, v41, v249
	v_add_f32_e32 v153, v42, v250
	v_add_f32_e32 v152, v43, v251
	v_add_f32_e32 v155, v44, v252
	v_add_f32_e32 v154, v45, v253
	v_add_f32_e32 v157, v46, v254
	v_add_f32_e32 v156, v47, v255
	v_max3_f32 v32, v142, s37, v141
	v_max3_f32 v32, v32, v145, v143
	v_max3_f32 v32, v32, v147, v146
	v_max3_f32 v32, v32, v149, v148
	v_max3_f32 v32, v32, v151, v150
	v_max3_f32 v32, v32, v153, v152
	v_max3_f32 v32, v32, v155, v154
	v_max3_f32 v32, v32, v157, v156
	v_mov_b32_e32 v33, v32
	s_nop 1
	v_permlane32_swap_b32_e32 v32, v33
	v_max_f32_e32 v33, v33, v33
	v_max_f32_e32 v32, v32, v32
	v_max_f32_e32 v159, v32, v33
	v_add_f32_e32 v32, 0x40b00000, v139
	v_cmp_gt_f32_e32 vcc, v159, v32
	v_mov_b64_e32 v[62:63], v[30:31]
	v_mov_b64_e32 v[60:61], v[28:29]
	v_mov_b64_e32 v[58:59], v[26:27]
	v_mov_b64_e32 v[56:57], v[24:25]
	v_mov_b64_e32 v[54:55], v[22:23]
	v_mov_b64_e32 v[52:53], v[20:21]
	v_mov_b64_e32 v[50:51], v[18:19]
	v_mov_b64_e32 v[48:49], v[16:17]
	v_mov_b64_e32 v[46:47], v[14:15]
	v_mov_b64_e32 v[44:45], v[12:13]
	v_mov_b64_e32 v[42:43], v[10:11]
	v_mov_b64_e32 v[40:41], v[8:9]
	v_mov_b64_e32 v[38:39], v[6:7]
	v_mov_b64_e32 v[36:37], v[4:5]
	v_mov_b64_e32 v[34:35], v[2:3]
	v_mov_b64_e32 v[32:33], v[0:1]
	v_mov_b32_e32 v158, v140
	v_mov_b32_e32 v144, v139
	s_cbranch_vccz .LBB0_1122
	v_cndmask_b32_e32 v144, v139, v159, vcc
	v_sub_f32_e32 v32, v139, v144
	v_mul_f32_e32 v32, 0x3fb8aa3b, v32
	v_exp_f32_e32 v158, v32
	s_nop 0
	v_pk_mul_f32 v[62:63], v[30:31], v[158:159] op_sel_hi:[1,0]
	v_pk_mul_f32 v[60:61], v[28:29], v[158:159] op_sel_hi:[1,0]
	v_pk_mul_f32 v[58:59], v[26:27], v[158:159] op_sel_hi:[1,0]
	v_pk_mul_f32 v[56:57], v[24:25], v[158:159] op_sel_hi:[1,0]
	v_pk_mul_f32 v[54:55], v[22:23], v[158:159] op_sel_hi:[1,0]
	v_pk_mul_f32 v[52:53], v[20:21], v[158:159] op_sel_hi:[1,0]
	v_pk_mul_f32 v[50:51], v[18:19], v[158:159] op_sel_hi:[1,0]
	v_pk_mul_f32 v[48:49], v[16:17], v[158:159] op_sel_hi:[1,0]
	v_pk_mul_f32 v[46:47], v[14:15], v[158:159] op_sel_hi:[1,0]
	v_pk_mul_f32 v[44:45], v[12:13], v[158:159] op_sel_hi:[1,0]
	v_pk_mul_f32 v[42:43], v[10:11], v[158:159] op_sel_hi:[1,0]
	v_pk_mul_f32 v[40:41], v[8:9], v[158:159] op_sel_hi:[1,0]
	v_pk_mul_f32 v[38:39], v[6:7], v[158:159] op_sel_hi:[1,0]
	v_pk_mul_f32 v[36:37], v[4:5], v[158:159] op_sel_hi:[1,0]
	v_pk_mul_f32 v[34:35], v[2:3], v[158:159] op_sel_hi:[1,0]
	v_pk_mul_f32 v[32:33], v[0:1], v[158:159] op_sel_hi:[1,0]
	v_mul_f32_e32 v158, v140, v158
